# v37: v20 + conv LayerNorm wave sums via DPP/permlane swaps instead of ds_bpermute chains, LN gain/bias resident across units, dead address arithmetic and per-unit weight copies removed from the conv F
# speedup vs baseline: 1.0053x; 1.0053x over previous
; __device__ __forceinline__ void conv_phase(LAS unsigned char* lds, const bf16_t* P, const float* cw, const float* cb, const float* ng, const float* nb, bf16_t* CAT, int bid, int G, const int tid) {
;     ...
;             const int c = tid & 127, tb = tid >> 7;
;             float wj[31];
; #pragma unroll
;             for (int j = 0; j < 31; ++j) wj[j] = cw[j * 1024 + g * 128 + c];
;             const float bias = cb[g * 128 + c];
;             float acc[16];
; #pragma unroll
;             for (int o = 0; o < 16; ++o) acc[o] = bias;
; #pragma unroll
;             for (int i = 0; i < 46; ++i) {
;                 const float z = zs[(tb * 16 + i) * 128 + c];
; #pragma unroll
;                 for (int o = 0; o < 16; ++o) { const int j = i - o; if (j >= 0 && j <= 30) acc[o] += wj[j] * z; }
.LBB0_170:
	s_and_b32 s30, s35, 0x380
	s_cmp_eq_u32 s30, s63
	s_cbranch_scc1 .Lconv_wok
	s_mov_b32 s63, s30
	v_or_b32_e32 v226, s30, v39
	v_lshlrev_b32_e32 v226, 2, v226
	s_mov_b64 s[64:65], s[4:5]
	global_load_dword v194, v226, s[64:65]
	s_add_u32 s64, s64, 0x1000
	s_addc_u32 s65, s65, 0
	global_load_dword v195, v226, s[64:65]
	s_add_u32 s64, s64, 0x1000
	s_addc_u32 s65, s65, 0
	global_load_dword v196, v226, s[64:65]
	s_add_u32 s64, s64, 0x1000
	s_addc_u32 s65, s65, 0
	global_load_dword v197, v226, s[64:65]
	s_add_u32 s64, s64, 0x1000
	s_addc_u32 s65, s65, 0
	global_load_dword v198, v226, s[64:65]
	s_add_u32 s64, s64, 0x1000
	s_addc_u32 s65, s65, 0
	global_load_dword v199, v226, s[64:65]
	s_add_u32 s64, s64, 0x1000
	s_addc_u32 s65, s65, 0
	global_load_dword v200, v226, s[64:65]
	s_add_u32 s64, s64, 0x1000
	s_addc_u32 s65, s65, 0
	global_load_dword v201, v226, s[64:65]
	s_add_u32 s64, s64, 0x1000
	s_addc_u32 s65, s65, 0
	global_load_dword v202, v226, s[64:65]
	s_add_u32 s64, s64, 0x1000
	s_addc_u32 s65, s65, 0
	global_load_dword v203, v226, s[64:65]
	s_add_u32 s64, s64, 0x1000
	s_addc_u32 s65, s65, 0
	global_load_dword v204, v226, s[64:65]
	s_add_u32 s64, s64, 0x1000
	s_addc_u32 s65, s65, 0
	global_load_dword v205, v226, s[64:65]
	s_add_u32 s64, s64, 0x1000
	s_addc_u32 s65, s65, 0
	global_load_dword v206, v226, s[64:65]
	s_add_u32 s64, s64, 0x1000
	s_addc_u32 s65, s65, 0
	global_load_dword v207, v226, s[64:65]
	s_add_u32 s64, s64, 0x1000
	s_addc_u32 s65, s65, 0
	global_load_dword v208, v226, s[64:65]
	s_add_u32 s64, s64, 0x1000
	s_addc_u32 s65, s65, 0
	global_load_dword v209, v226, s[64:65]
	s_add_u32 s64, s64, 0x1000
	s_addc_u32 s65, s65, 0
	global_load_dword v210, v226, s[64:65]
	s_add_u32 s64, s64, 0x1000
	s_addc_u32 s65, s65, 0
	global_load_dword v211, v226, s[64:65]
	s_add_u32 s64, s64, 0x1000
	s_addc_u32 s65, s65, 0
	global_load_dword v212, v226, s[64:65]
	s_add_u32 s64, s64, 0x1000
	s_addc_u32 s65, s65, 0
	global_load_dword v213, v226, s[64:65]
	s_add_u32 s64, s64, 0x1000
	s_addc_u32 s65, s65, 0
	global_load_dword v214, v226, s[64:65]
	s_add_u32 s64, s64, 0x1000
	s_addc_u32 s65, s65, 0
	global_load_dword v215, v226, s[64:65]
	s_add_u32 s64, s64, 0x1000
	s_addc_u32 s65, s65, 0
	global_load_dword v216, v226, s[64:65]
	s_add_u32 s64, s64, 0x1000
	s_addc_u32 s65, s65, 0
	global_load_dword v217, v226, s[64:65]
	s_add_u32 s64, s64, 0x1000
	s_addc_u32 s65, s65, 0
	global_load_dword v218, v226, s[64:65]
	s_add_u32 s64, s64, 0x1000
	s_addc_u32 s65, s65, 0
	global_load_dword v219, v226, s[64:65]
	s_add_u32 s64, s64, 0x1000
	s_addc_u32 s65, s65, 0
	global_load_dword v220, v226, s[64:65]
	s_add_u32 s64, s64, 0x1000
	s_addc_u32 s65, s65, 0
	global_load_dword v221, v226, s[64:65]
	s_add_u32 s64, s64, 0x1000
	s_addc_u32 s65, s65, 0
	global_load_dword v222, v226, s[64:65]
	s_add_u32 s64, s64, 0x1000
	s_addc_u32 s65, s65, 0
	global_load_dword v223, v226, s[64:65]
	s_add_u32 s64, s64, 0x1000
	s_addc_u32 s65, s65, 0
	global_load_dword v224, v226, s[64:65]
	global_load_dword v225, v226, s[6:7]
	s_lshl_b32 s64, s30, 2
	s_mov_b32 s65, 0
	v_lshl_add_u64 v[154:155], v[26:27], 0, s[64:65]
	global_load_dwordx2 v[150:151], v[154:155], off
	v_lshl_add_u64 v[154:155], v[28:29], 0, s[64:65]
	global_load_dwordx2 v[152:153], v[154:155], off
	s_waitcnt vmcnt(0)
.Lconv_wok:
	v_or_b32_e32 v31, s30, v39
	v_lshlrev_b32_e32 v176, 2, v31
	ds_read2st64_b32 v[90:91], v40 offset0:12 offset1:14
	ds_read2st64_b32 v[94:95], v40 offset0:16 offset1:18
	ds_read2st64_b32 v[98:99], v40 offset0:20 offset1:22
	ds_read2st64_b32 v[102:103], v40 offset0:24 offset1:26
	ds_read2st64_b32 v[108:109], v40 offset0:28 offset1:30
	s_and_b32 s31, s34, 0xffffffc0
	s_mov_b32 s34, s15
	s_mov_b32 s35, s17
	v_mov_b32_e32 v31, v223
	ds_read2st64_b32 v[74:75], v40 offset1:2
	v_mov_b32_e32 v33, v225
	ds_read2st64_b32 v[86:87], v40 offset0:4 offset1:6
	s_lshl_b32 s26, s30, 2
	s_andn2_b64 vcc, exec, s[20:21]
	s_waitcnt lgkmcnt(0)
	v_fma_f32 v74, v194, v74, v33
	v_fmac_f32_e32 v74, v195, v75
	v_fma_f32 v75, v194, v75, v33
	v_fmac_f32_e32 v74, v196, v86
	v_fmac_f32_e32 v75, v195, v86
	v_fma_f32 v83, v194, v86, v33
	v_fmac_f32_e32 v74, v197, v87
	v_fmac_f32_e32 v75, v196, v87
	v_fmac_f32_e32 v83, v195, v87
	v_fma_f32 v84, v194, v87, v33
	ds_read2st64_b32 v[86:87], v40 offset0:8 offset1:10
	v_fma_f32 v106, v194, v108, v33
	v_fmac_f32_e32 v106, v195, v109
	s_waitcnt lgkmcnt(0)
; __device__ __forceinline__ void conv_phase(LAS unsigned char* lds, const bf16_t* P, const float* cw, const float* cb, const float* ng, const float* nb, bf16_t* CAT, int bid, int G, const int tid) {
;     ...
;             for (int i = 0; i < 46; ++i) {
;                 const float z = zs[(tb * 16 + i) * 128 + c];
; #pragma unroll
;                 for (int o = 0; o < 16; ++o) { const int j = i - o; if (j >= 0 && j <= 30) acc[o] += wj[j] * z; }
	v_fmac_f32_e32 v74, v198, v86
	v_fmac_f32_e32 v75, v197, v86
	v_fmac_f32_e32 v83, v196, v86
	v_fmac_f32_e32 v84, v195, v86
	v_fma_f32 v86, v194, v86, v33
	v_fmac_f32_e32 v74, v199, v87
	v_fmac_f32_e32 v75, v198, v87
	v_fmac_f32_e32 v83, v197, v87
	v_fmac_f32_e32 v84, v196, v87
	v_fmac_f32_e32 v86, v195, v87
	v_fma_f32 v87, v194, v87, v33
	v_fmac_f32_e32 v74, v200, v90
	v_fmac_f32_e32 v75, v199, v90
	v_fmac_f32_e32 v83, v198, v90
	v_fmac_f32_e32 v84, v197, v90
	v_fmac_f32_e32 v86, v196, v90
	v_fmac_f32_e32 v87, v195, v90
	v_fma_f32 v90, v194, v90, v33
	v_fmac_f32_e32 v74, v201, v91
	v_fmac_f32_e32 v75, v200, v91
	v_fmac_f32_e32 v83, v199, v91
	v_fmac_f32_e32 v84, v198, v91
	v_fmac_f32_e32 v86, v197, v91
	v_fmac_f32_e32 v87, v196, v91
	v_fmac_f32_e32 v90, v195, v91
	v_fma_f32 v91, v194, v91, v33
	v_fmac_f32_e32 v74, v202, v94
	v_fmac_f32_e32 v75, v201, v94
	v_fmac_f32_e32 v83, v200, v94
	v_fmac_f32_e32 v84, v199, v94
	v_fmac_f32_e32 v86, v198, v94
	v_fmac_f32_e32 v87, v197, v94
	v_fmac_f32_e32 v90, v196, v94
	v_fmac_f32_e32 v91, v195, v94
	v_fma_f32 v94, v194, v94, v33
	v_fmac_f32_e32 v74, v203, v95
	v_fmac_f32_e32 v75, v202, v95
	v_fmac_f32_e32 v83, v201, v95
	v_fmac_f32_e32 v84, v200, v95
	v_fmac_f32_e32 v86, v199, v95
	v_fmac_f32_e32 v87, v198, v95
	v_fmac_f32_e32 v90, v197, v95
	v_fmac_f32_e32 v91, v196, v95
	v_fmac_f32_e32 v94, v195, v95
	v_fma_f32 v95, v194, v95, v33
	v_fmac_f32_e32 v74, v204, v98
	v_fmac_f32_e32 v75, v203, v98
	v_fmac_f32_e32 v83, v202, v98
	v_fmac_f32_e32 v84, v201, v98
	v_fmac_f32_e32 v86, v200, v98
	v_fmac_f32_e32 v87, v199, v98
	v_fmac_f32_e32 v90, v198, v98
	v_fmac_f32_e32 v91, v197, v98
	v_fmac_f32_e32 v94, v196, v98
	v_fmac_f32_e32 v95, v195, v98
	v_fma_f32 v98, v194, v98, v33
	v_fmac_f32_e32 v74, v205, v99
	v_fmac_f32_e32 v75, v204, v99
	v_fmac_f32_e32 v83, v203, v99
	v_fmac_f32_e32 v84, v202, v99
	v_fmac_f32_e32 v86, v201, v99
	v_fmac_f32_e32 v87, v200, v99
	v_fmac_f32_e32 v90, v199, v99
	v_fmac_f32_e32 v91, v198, v99
	v_fmac_f32_e32 v94, v197, v99
	v_fmac_f32_e32 v95, v196, v99
	v_fmac_f32_e32 v98, v195, v99
	v_fma_f32 v99, v194, v99, v33
	v_fmac_f32_e32 v74, v206, v102
	v_fmac_f32_e32 v75, v205, v102
	v_fmac_f32_e32 v83, v204, v102
	v_fmac_f32_e32 v84, v203, v102
	v_fmac_f32_e32 v86, v202, v102
	v_fmac_f32_e32 v87, v201, v102
	v_fmac_f32_e32 v90, v200, v102
	v_fmac_f32_e32 v91, v199, v102
	v_fmac_f32_e32 v94, v198, v102
	v_fmac_f32_e32 v95, v197, v102
	v_fmac_f32_e32 v98, v196, v102
	v_fmac_f32_e32 v99, v195, v102
	v_fma_f32 v102, v194, v102, v33
	v_fmac_f32_e32 v74, v207, v103
	v_fmac_f32_e32 v75, v206, v103
	v_fmac_f32_e32 v83, v205, v103
	v_fmac_f32_e32 v84, v204, v103
	v_fmac_f32_e32 v86, v203, v103
	v_fmac_f32_e32 v87, v202, v103
	v_fmac_f32_e32 v90, v201, v103
	v_fmac_f32_e32 v91, v200, v103
	v_fmac_f32_e32 v94, v199, v103
	v_fmac_f32_e32 v95, v198, v103
	v_fmac_f32_e32 v98, v197, v103
	v_fmac_f32_e32 v99, v196, v103
	v_fmac_f32_e32 v102, v195, v103
	v_fma_f32 v103, v194, v103, v33
	v_fmac_f32_e32 v74, v208, v108
	v_fmac_f32_e32 v75, v207, v108
	v_fmac_f32_e32 v83, v206, v108
	v_fmac_f32_e32 v84, v205, v108
	v_fmac_f32_e32 v86, v204, v108
	v_fmac_f32_e32 v87, v203, v108
	v_fmac_f32_e32 v90, v202, v108
	v_fmac_f32_e32 v91, v201, v108
	v_fmac_f32_e32 v94, v200, v108
	v_fmac_f32_e32 v95, v199, v108
	v_fmac_f32_e32 v98, v198, v108
	v_fmac_f32_e32 v99, v197, v108
	v_fmac_f32_e32 v102, v196, v108
	v_fmac_f32_e32 v103, v195, v108
	v_fmac_f32_e32 v74, v209, v109
	v_fmac_f32_e32 v75, v208, v109
	v_fmac_f32_e32 v83, v207, v109
	v_fmac_f32_e32 v84, v206, v109
	v_fmac_f32_e32 v86, v205, v109
	v_fmac_f32_e32 v87, v204, v109
	v_fmac_f32_e32 v90, v203, v109
	v_fmac_f32_e32 v91, v202, v109
	v_fmac_f32_e32 v94, v201, v109
	v_fmac_f32_e32 v95, v200, v109
	v_fmac_f32_e32 v98, v199, v109
	v_fmac_f32_e32 v99, v198, v109
	v_fmac_f32_e32 v102, v197, v109
	v_fmac_f32_e32 v103, v196, v109
	v_fmac_f32_e32 v33, v194, v109
	ds_read2st64_b32 v[108:109], v40 offset0:32 offset1:34
	s_waitcnt lgkmcnt(0)
	v_fmac_f32_e32 v33, v195, v108
	v_fmac_f32_e32 v106, v196, v108
	v_fmac_f32_e32 v33, v196, v109
	ds_read2st64_b32 v[104:105], v40 offset0:36 offset1:38
	v_fmac_f32_e32 v103, v197, v108
	v_fmac_f32_e32 v106, v197, v109
	v_fmac_f32_e32 v102, v198, v108
	v_fmac_f32_e32 v103, v198, v109
	s_waitcnt lgkmcnt(0)
	v_fmac_f32_e32 v33, v197, v104
	v_fmac_f32_e32 v106, v198, v104
	v_fmac_f32_e32 v33, v198, v105
	ds_read2st64_b32 v[100:101], v40 offset0:40 offset1:42
	v_fmac_f32_e32 v99, v199, v108
	v_fmac_f32_e32 v102, v199, v109
	v_fmac_f32_e32 v103, v199, v104
	v_fmac_f32_e32 v106, v199, v105
	s_waitcnt lgkmcnt(0)
	v_fmac_f32_e32 v33, v199, v100
	v_fmac_f32_e32 v98, v200, v108
	v_fmac_f32_e32 v99, v200, v109
	v_fmac_f32_e32 v102, v200, v104
	v_fmac_f32_e32 v103, v200, v105
	v_fmac_f32_e32 v106, v200, v100
	v_fmac_f32_e32 v33, v200, v101
	ds_read2st64_b32 v[96:97], v40 offset0:44 offset1:46
	v_fmac_f32_e32 v95, v201, v108
	v_fmac_f32_e32 v98, v201, v109
	v_fmac_f32_e32 v99, v201, v104
	v_fmac_f32_e32 v102, v201, v105
	v_fmac_f32_e32 v103, v201, v100
	v_fmac_f32_e32 v106, v201, v101
	s_waitcnt lgkmcnt(0)
; __device__ __forceinline__ void conv_phase(LAS unsigned char* lds, const bf16_t* P, const float* cw, const float* cb, const float* ng, const float* nb, bf16_t* CAT, int bid, int G, const int tid) {
;     ...
;             for (int i = 0; i < 46; ++i) {
;                 const float z = zs[(tb * 16 + i) * 128 + c];
; #pragma unroll
;                 for (int o = 0; o < 16; ++o) { const int j = i - o; if (j >= 0 && j <= 30) acc[o] += wj[j] * z; }
	v_fmac_f32_e32 v33, v201, v96
	v_fmac_f32_e32 v94, v202, v108
	v_fmac_f32_e32 v95, v202, v109
	v_fmac_f32_e32 v98, v202, v104
	v_fmac_f32_e32 v99, v202, v105
	v_fmac_f32_e32 v102, v202, v100
	v_fmac_f32_e32 v103, v202, v101
	v_fmac_f32_e32 v106, v202, v96
	v_fmac_f32_e32 v33, v202, v97
	ds_read2st64_b32 v[92:93], v40 offset0:48 offset1:50
	v_fmac_f32_e32 v74, v210, v108
	v_fmac_f32_e32 v75, v209, v108
	v_fmac_f32_e32 v83, v208, v108
	v_fmac_f32_e32 v84, v207, v108
	v_fmac_f32_e32 v86, v206, v108
	v_fmac_f32_e32 v87, v205, v108
	v_fmac_f32_e32 v90, v204, v108
	v_fmac_f32_e32 v91, v203, v108
	v_fmac_f32_e32 v74, v211, v109
	v_fmac_f32_e32 v75, v210, v109
	v_fmac_f32_e32 v83, v209, v109
	v_fmac_f32_e32 v84, v208, v109
	v_fmac_f32_e32 v86, v207, v109
	v_fmac_f32_e32 v87, v206, v109
	v_fmac_f32_e32 v90, v205, v109
	v_fmac_f32_e32 v91, v204, v109
	v_fmac_f32_e32 v94, v203, v109
	v_fmac_f32_e32 v74, v212, v104
	v_fmac_f32_e32 v75, v211, v104
	v_fmac_f32_e32 v83, v210, v104
	v_fmac_f32_e32 v84, v209, v104
	v_fmac_f32_e32 v86, v208, v104
	v_fmac_f32_e32 v87, v207, v104
	v_fmac_f32_e32 v90, v206, v104
	v_fmac_f32_e32 v91, v205, v104
	v_fmac_f32_e32 v94, v204, v104
	v_fmac_f32_e32 v95, v203, v104
	v_fmac_f32_e32 v74, v213, v105
	v_fmac_f32_e32 v75, v212, v105
	v_fmac_f32_e32 v83, v211, v105
	v_fmac_f32_e32 v84, v210, v105
	v_fmac_f32_e32 v86, v209, v105
	v_fmac_f32_e32 v87, v208, v105
	v_fmac_f32_e32 v90, v207, v105
	v_fmac_f32_e32 v91, v206, v105
	v_fmac_f32_e32 v94, v205, v105
	v_fmac_f32_e32 v95, v204, v105
	v_fmac_f32_e32 v98, v203, v105
	v_fmac_f32_e32 v74, v214, v100
	v_fmac_f32_e32 v75, v213, v100
	v_fmac_f32_e32 v83, v212, v100
	v_fmac_f32_e32 v84, v211, v100
	v_fmac_f32_e32 v86, v210, v100
	v_fmac_f32_e32 v87, v209, v100
	v_fmac_f32_e32 v90, v208, v100
	v_fmac_f32_e32 v91, v207, v100
	v_fmac_f32_e32 v94, v206, v100
	v_fmac_f32_e32 v95, v205, v100
	v_fmac_f32_e32 v98, v204, v100
	v_fmac_f32_e32 v99, v203, v100
	v_fmac_f32_e32 v102, v203, v101
	v_fmac_f32_e32 v103, v203, v96
	v_fmac_f32_e32 v106, v203, v97
	s_waitcnt lgkmcnt(0)
	v_fmac_f32_e32 v33, v203, v92
	v_fmac_f32_e32 v74, v215, v101
	v_fmac_f32_e32 v75, v214, v101
	v_fmac_f32_e32 v83, v213, v101
	v_fmac_f32_e32 v84, v212, v101
	v_fmac_f32_e32 v86, v211, v101
	v_fmac_f32_e32 v87, v210, v101
	v_fmac_f32_e32 v90, v209, v101
	v_fmac_f32_e32 v91, v208, v101
	v_fmac_f32_e32 v94, v207, v101
	v_fmac_f32_e32 v95, v206, v101
	v_fmac_f32_e32 v98, v205, v101
	v_fmac_f32_e32 v99, v204, v101
	v_fmac_f32_e32 v102, v204, v96
	v_fmac_f32_e32 v103, v204, v97
	v_fmac_f32_e32 v106, v204, v92
	v_fmac_f32_e32 v33, v204, v93
	ds_read2st64_b32 v[88:89], v40 offset0:52 offset1:54
	v_fmac_f32_e32 v74, v216, v96
	v_fmac_f32_e32 v75, v215, v96
	v_fmac_f32_e32 v83, v214, v96
	v_fmac_f32_e32 v84, v213, v96
	v_fmac_f32_e32 v86, v212, v96
	v_fmac_f32_e32 v87, v211, v96
	v_fmac_f32_e32 v90, v210, v96
	v_fmac_f32_e32 v91, v209, v96
	v_fmac_f32_e32 v94, v208, v96
	v_fmac_f32_e32 v95, v207, v96
	v_fmac_f32_e32 v98, v206, v96
	v_fmac_f32_e32 v99, v205, v96
	v_fmac_f32_e32 v74, v217, v97
	v_fmac_f32_e32 v75, v216, v97
	v_fmac_f32_e32 v83, v215, v97
	v_fmac_f32_e32 v84, v214, v97
	v_fmac_f32_e32 v86, v213, v97
	v_fmac_f32_e32 v87, v212, v97
	v_fmac_f32_e32 v90, v211, v97
	v_fmac_f32_e32 v91, v210, v97
	v_fmac_f32_e32 v94, v209, v97
	v_fmac_f32_e32 v95, v208, v97
	v_fmac_f32_e32 v98, v207, v97
	v_fmac_f32_e32 v99, v206, v97
	v_fmac_f32_e32 v102, v205, v97
	v_fmac_f32_e32 v74, v218, v92
	v_fmac_f32_e32 v75, v217, v92
	v_fmac_f32_e32 v83, v216, v92
	v_fmac_f32_e32 v84, v215, v92
	v_fmac_f32_e32 v86, v214, v92
	v_fmac_f32_e32 v87, v213, v92
	v_fmac_f32_e32 v90, v212, v92
	v_fmac_f32_e32 v91, v211, v92
	v_fmac_f32_e32 v94, v210, v92
	v_fmac_f32_e32 v95, v209, v92
	v_fmac_f32_e32 v98, v208, v92
	v_fmac_f32_e32 v99, v207, v92
	v_fmac_f32_e32 v102, v206, v92
	v_fmac_f32_e32 v103, v205, v92
	v_fmac_f32_e32 v74, v219, v93
	v_fmac_f32_e32 v75, v218, v93
	v_fmac_f32_e32 v83, v217, v93
	v_fmac_f32_e32 v84, v216, v93
	v_fmac_f32_e32 v86, v215, v93
	v_fmac_f32_e32 v87, v214, v93
	v_fmac_f32_e32 v90, v213, v93
	v_fmac_f32_e32 v91, v212, v93
	v_fmac_f32_e32 v94, v211, v93
	v_fmac_f32_e32 v95, v210, v93
	v_fmac_f32_e32 v98, v209, v93
	v_fmac_f32_e32 v99, v208, v93
	v_fmac_f32_e32 v102, v207, v93
	v_fmac_f32_e32 v103, v206, v93
	v_fmac_f32_e32 v106, v205, v93
	s_waitcnt lgkmcnt(0)
	v_fmac_f32_e32 v74, v220, v88
	v_fmac_f32_e32 v75, v219, v88
	v_fmac_f32_e32 v83, v218, v88
	v_fmac_f32_e32 v84, v217, v88
	v_fmac_f32_e32 v86, v216, v88
	v_fmac_f32_e32 v87, v215, v88
	v_fmac_f32_e32 v90, v214, v88
	v_fmac_f32_e32 v91, v213, v88
	v_fmac_f32_e32 v94, v212, v88
	v_fmac_f32_e32 v95, v211, v88
	v_fmac_f32_e32 v98, v210, v88
	v_fmac_f32_e32 v99, v209, v88
	v_fmac_f32_e32 v102, v208, v88
	v_fmac_f32_e32 v103, v207, v88
	v_fmac_f32_e32 v106, v206, v88
	v_fmac_f32_e32 v33, v205, v88
	v_fmac_f32_e32 v74, v221, v89
	v_fmac_f32_e32 v75, v220, v89
	v_fmac_f32_e32 v83, v219, v89
	v_fmac_f32_e32 v84, v218, v89
	v_fmac_f32_e32 v86, v217, v89
	v_fmac_f32_e32 v87, v216, v89
	v_fmac_f32_e32 v90, v215, v89
	v_fmac_f32_e32 v91, v214, v89
	v_fmac_f32_e32 v94, v213, v89
	v_fmac_f32_e32 v95, v212, v89
	v_fmac_f32_e32 v98, v211, v89
	v_fmac_f32_e32 v99, v210, v89
	v_fmac_f32_e32 v102, v209, v89
	v_fmac_f32_e32 v103, v208, v89
	v_fmac_f32_e32 v106, v207, v89
	v_fmac_f32_e32 v33, v206, v89
	ds_read2st64_b32 v[88:89], v40 offset0:56 offset1:58
	s_waitcnt lgkmcnt(0)
	v_fmac_f32_e32 v33, v207, v88
	v_fmac_f32_e32 v106, v208, v88
	v_fmac_f32_e32 v33, v208, v89
	ds_read2st64_b32 v[80:81], v40 offset0:60 offset1:62
	v_fmac_f32_e32 v103, v209, v88
	v_fmac_f32_e32 v106, v209, v89
	v_fmac_f32_e32 v102, v210, v88
	v_fmac_f32_e32 v103, v210, v89
	s_waitcnt lgkmcnt(0)
; __device__ __forceinline__ void conv_phase(LAS unsigned char* lds, const bf16_t* P, const float* cw, const float* cb, const float* ng, const float* nb, bf16_t* CAT, int bid, int G, const int tid) {
;     ...
;             for (int i = 0; i < 46; ++i) {
;                 const float z = zs[(tb * 16 + i) * 128 + c];
; #pragma unroll
;                 for (int o = 0; o < 16; ++o) { const int j = i - o; if (j >= 0 && j <= 30) acc[o] += wj[j] * z; }
;             }
; #pragma unroll
;             for (int o = 0; o < 16; ++o) co[(tb * 16 + o) * 128 + c] = acc[o];
;         }
;         __syncthreads();
	v_fmac_f32_e32 v33, v209, v80
	v_fmac_f32_e32 v106, v210, v80
	v_fmac_f32_e32 v33, v210, v81
	ds_read2st64_b32 v[78:79], v40 offset0:64 offset1:66
	v_fmac_f32_e32 v99, v211, v88
	v_fmac_f32_e32 v102, v211, v89
	v_fmac_f32_e32 v103, v211, v80
	v_fmac_f32_e32 v106, v211, v81
	s_waitcnt lgkmcnt(0)
	v_fmac_f32_e32 v33, v211, v78
	v_fmac_f32_e32 v98, v212, v88
	v_fmac_f32_e32 v99, v212, v89
	v_fmac_f32_e32 v102, v212, v80
	v_fmac_f32_e32 v103, v212, v81
	v_fmac_f32_e32 v106, v212, v78
	v_fmac_f32_e32 v33, v212, v79
	ds_read2st64_b32 v[76:77], v40 offset0:68 offset1:70
	v_fmac_f32_e32 v95, v213, v88
	v_fmac_f32_e32 v98, v213, v89
	v_fmac_f32_e32 v99, v213, v80
	v_fmac_f32_e32 v102, v213, v81
	v_fmac_f32_e32 v103, v213, v78
	v_fmac_f32_e32 v106, v213, v79
	s_waitcnt lgkmcnt(0)
	v_fmac_f32_e32 v33, v213, v76
	v_fmac_f32_e32 v94, v214, v88
	v_fmac_f32_e32 v95, v214, v89
	v_fmac_f32_e32 v98, v214, v80
	v_fmac_f32_e32 v99, v214, v81
	v_fmac_f32_e32 v102, v214, v78
	v_fmac_f32_e32 v103, v214, v79
	v_fmac_f32_e32 v106, v214, v76
	v_fmac_f32_e32 v33, v214, v77
	ds_read2st64_b32 v[72:73], v40 offset0:72 offset1:74
	v_fmac_f32_e32 v91, v215, v88
	v_fmac_f32_e32 v94, v215, v89
	v_fmac_f32_e32 v95, v215, v80
	v_fmac_f32_e32 v98, v215, v81
	v_fmac_f32_e32 v99, v215, v78
	v_fmac_f32_e32 v102, v215, v79
	v_fmac_f32_e32 v103, v215, v76
	v_fmac_f32_e32 v106, v215, v77
	s_waitcnt lgkmcnt(0)
	v_fmac_f32_e32 v33, v215, v72
	v_fmac_f32_e32 v90, v216, v88
	v_fmac_f32_e32 v91, v216, v89
	v_fmac_f32_e32 v94, v216, v80
	v_fmac_f32_e32 v95, v216, v81
	v_fmac_f32_e32 v98, v216, v78
	v_fmac_f32_e32 v99, v216, v79
	v_fmac_f32_e32 v102, v216, v76
	v_fmac_f32_e32 v103, v216, v77
	v_fmac_f32_e32 v106, v216, v72
	v_fmac_f32_e32 v33, v216, v73
	ds_read2st64_b32 v[70:71], v40 offset0:76 offset1:78
	v_fmac_f32_e32 v87, v217, v88
	v_fmac_f32_e32 v90, v217, v89
	v_fmac_f32_e32 v91, v217, v80
	v_fmac_f32_e32 v94, v217, v81
	v_fmac_f32_e32 v95, v217, v78
	v_fmac_f32_e32 v98, v217, v79
	v_fmac_f32_e32 v99, v217, v76
	v_fmac_f32_e32 v102, v217, v77
	v_fmac_f32_e32 v103, v217, v72
	v_fmac_f32_e32 v106, v217, v73
	s_waitcnt lgkmcnt(0)
	v_fmac_f32_e32 v33, v217, v70
	v_fmac_f32_e32 v86, v218, v88
	v_fmac_f32_e32 v87, v218, v89
	v_fmac_f32_e32 v90, v218, v80
	v_fmac_f32_e32 v91, v218, v81
	v_fmac_f32_e32 v94, v218, v78
	v_fmac_f32_e32 v95, v218, v79
	v_fmac_f32_e32 v98, v218, v76
	v_fmac_f32_e32 v99, v218, v77
	v_fmac_f32_e32 v102, v218, v72
	v_fmac_f32_e32 v103, v218, v73
	v_fmac_f32_e32 v106, v218, v70
	v_fmac_f32_e32 v33, v218, v71
	ds_read2st64_b32 v[68:69], v40 offset0:80 offset1:82
	v_fmac_f32_e32 v84, v219, v88
	v_fmac_f32_e32 v86, v219, v89
	v_fmac_f32_e32 v87, v219, v80
	v_fmac_f32_e32 v90, v219, v81
	v_fmac_f32_e32 v91, v219, v78
	v_fmac_f32_e32 v94, v219, v79
	v_fmac_f32_e32 v95, v219, v76
	v_fmac_f32_e32 v98, v219, v77
	v_fmac_f32_e32 v99, v219, v72
	v_fmac_f32_e32 v102, v219, v73
	v_fmac_f32_e32 v103, v219, v70
	v_fmac_f32_e32 v106, v219, v71
	s_waitcnt lgkmcnt(0)
	v_fmac_f32_e32 v33, v219, v68
	v_fmac_f32_e32 v83, v220, v88
	v_fmac_f32_e32 v84, v220, v89
	v_fmac_f32_e32 v86, v220, v80
	v_fmac_f32_e32 v87, v220, v81
	v_fmac_f32_e32 v90, v220, v78
	v_fmac_f32_e32 v91, v220, v79
	v_fmac_f32_e32 v94, v220, v76
	v_fmac_f32_e32 v95, v220, v77
	v_fmac_f32_e32 v98, v220, v72
	v_fmac_f32_e32 v99, v220, v73
	v_fmac_f32_e32 v102, v220, v70
	v_fmac_f32_e32 v103, v220, v71
	v_fmac_f32_e32 v106, v220, v68
	v_fmac_f32_e32 v33, v220, v69
	ds_read2st64_b32 v[66:67], v40 offset0:84 offset1:86
	v_fmac_f32_e32 v75, v221, v88
	v_fmac_f32_e32 v83, v221, v89
	v_fmac_f32_e32 v84, v221, v80
	v_fmac_f32_e32 v86, v221, v81
	v_fmac_f32_e32 v87, v221, v78
	v_fmac_f32_e32 v90, v221, v79
	v_fmac_f32_e32 v91, v221, v76
	v_fmac_f32_e32 v94, v221, v77
	v_fmac_f32_e32 v95, v221, v72
	v_fmac_f32_e32 v98, v221, v73
	v_fmac_f32_e32 v99, v221, v70
	v_fmac_f32_e32 v102, v221, v71
	v_fmac_f32_e32 v103, v221, v68
	v_fmac_f32_e32 v106, v221, v69
	s_waitcnt lgkmcnt(0)
	v_fmac_f32_e32 v33, v221, v66
	v_fmac_f32_e32 v74, v222, v88
	v_fmac_f32_e32 v75, v222, v89
	v_fmac_f32_e32 v83, v222, v80
	v_fmac_f32_e32 v84, v222, v81
	v_fmac_f32_e32 v86, v222, v78
	v_fmac_f32_e32 v87, v222, v79
	v_fmac_f32_e32 v90, v222, v76
	v_fmac_f32_e32 v91, v222, v77
	v_fmac_f32_e32 v94, v222, v72
	v_fmac_f32_e32 v95, v222, v73
	v_fmac_f32_e32 v98, v222, v70
	v_fmac_f32_e32 v99, v222, v71
	v_fmac_f32_e32 v102, v222, v68
	v_fmac_f32_e32 v103, v222, v69
	v_fmac_f32_e32 v106, v222, v66
	v_fmac_f32_e32 v33, v222, v67
	ds_read2st64_b32 v[34:35], v40 offset0:88 offset1:90
	v_fmac_f32_e32 v74, v31, v89
	v_fmac_f32_e32 v75, v31, v80
	v_fmac_f32_e32 v74, v224, v80
	v_fmac_f32_e32 v75, v224, v81
	v_fmac_f32_e32 v83, v31, v81
	v_fmac_f32_e32 v84, v31, v78
	v_fmac_f32_e32 v86, v31, v79
	v_fmac_f32_e32 v87, v31, v76
	v_fmac_f32_e32 v90, v31, v77
	v_fmac_f32_e32 v91, v31, v72
	v_fmac_f32_e32 v94, v31, v73
	v_fmac_f32_e32 v95, v31, v70
	v_fmac_f32_e32 v98, v31, v71
	v_fmac_f32_e32 v99, v31, v68
	v_fmac_f32_e32 v102, v31, v69
	v_fmac_f32_e32 v103, v31, v66
	v_fmac_f32_e32 v106, v31, v67
	s_waitcnt lgkmcnt(0)
	v_fmac_f32_e32 v33, v31, v34
	v_fmac_f32_e32 v83, v224, v78
	v_fmac_f32_e32 v84, v224, v79
	v_fmac_f32_e32 v86, v224, v76
	v_fmac_f32_e32 v87, v224, v77
	v_fmac_f32_e32 v90, v224, v72
	v_fmac_f32_e32 v91, v224, v73
	v_fmac_f32_e32 v94, v224, v70
	v_fmac_f32_e32 v95, v224, v71
	v_fmac_f32_e32 v98, v224, v68
	v_fmac_f32_e32 v99, v224, v69
	v_fmac_f32_e32 v102, v224, v66
	v_fmac_f32_e32 v103, v224, v67
	v_fmac_f32_e32 v106, v224, v34
	v_fmac_f32_e32 v33, v224, v35
	ds_write2st64_b32 v40, v74, v75 offset0:188 offset1:190
	ds_write2st64_b32 v40, v83, v84 offset0:192 offset1:194
	ds_write2st64_b32 v40, v86, v87 offset0:196 offset1:198
	ds_write2st64_b32 v40, v90, v91 offset0:200 offset1:202
	ds_write2st64_b32 v40, v94, v95 offset0:204 offset1:206
	ds_write2st64_b32 v40, v98, v99 offset0:208 offset1:210
	ds_write2st64_b32 v40, v102, v103 offset0:212 offset1:214
	ds_write2st64_b32 v40, v106, v33 offset0:216 offset1:218
	s_waitcnt lgkmcnt(0)
	s_barrier
; #define LAS __attribute__((address_space(3)))
; __device__ __forceinline__ void conv_phase(LAS unsigned char* lds, const bf16_t* P, const float* cw, const float* cb, const float* ng, const float* nb, bf16_t* CAT, int bid, int G, const int tid) {
;     ...
;             const f32x2 gg = *(const f32x2*)(ng + g * 128 + 2 * lane), bb = *(const f32x2*)(nb + g * 128 + 2 * lane);
; #pragma unroll
;             for (int k = 0; k < 8; ++k) {
;                 const int tok = w * 8 + k;
;                 const f32x2 v = *(const LAS f32x2*)(co + tok * 128 + 2 * lane);
;                 const float mean = wave_sum(v[0] + v[1]) * (1.0f / 128.0f);
;                 const float d0 = v[0] - mean, d1 = v[1] - mean;
;                 const float rs = __builtin_amdgcn_rsqf(wave_sum(d0 * d0 + d1 * d1) * (1.0f / 128.0f) + EPS);
	s_lshl_b32 s26, s30, 1
	v_mov_b32_e32 v31, v177
	ds_read_b64 v[110:111], v58 offset:48128
	ds_read_b64 v[112:113], v59 offset:48128
	ds_read_b64 v[114:115], v60 offset:48128
	ds_read_b64 v[116:117], v61 offset:48128
	ds_read_b64 v[118:119], v62 offset:48128
	ds_read_b64 v[120:121], v63 offset:48128
	ds_read_b64 v[122:123], v64 offset:48128
	ds_read_b64 v[124:125], v65 offset:48128
	s_waitcnt lgkmcnt(7)
	v_add_f32_e32 v126, v110, v111
	s_waitcnt lgkmcnt(6)
	v_add_f32_e32 v127, v112, v113
	s_waitcnt lgkmcnt(5)
	v_add_f32_e32 v128, v114, v115
	s_waitcnt lgkmcnt(4)
	v_add_f32_e32 v129, v116, v117
	s_waitcnt lgkmcnt(3)
	v_add_f32_e32 v130, v118, v119
	s_waitcnt lgkmcnt(2)
	v_add_f32_e32 v131, v120, v121
	s_waitcnt lgkmcnt(1)
	v_add_f32_e32 v132, v122, v123
	s_waitcnt lgkmcnt(0)
	v_add_f32_e32 v133, v124, v125
	v_add_f32_dpp v126, v126, v126 quad_perm:[1,0,3,2] row_mask:0xf bank_mask:0xf
	v_add_f32_dpp v127, v127, v127 quad_perm:[1,0,3,2] row_mask:0xf bank_mask:0xf
	v_add_f32_dpp v128, v128, v128 quad_perm:[1,0,3,2] row_mask:0xf bank_mask:0xf
	v_add_f32_dpp v129, v129, v129 quad_perm:[1,0,3,2] row_mask:0xf bank_mask:0xf
	v_add_f32_dpp v130, v130, v130 quad_perm:[1,0,3,2] row_mask:0xf bank_mask:0xf
	v_add_f32_dpp v131, v131, v131 quad_perm:[1,0,3,2] row_mask:0xf bank_mask:0xf
	v_add_f32_dpp v132, v132, v132 quad_perm:[1,0,3,2] row_mask:0xf bank_mask:0xf
	v_add_f32_dpp v133, v133, v133 quad_perm:[1,0,3,2] row_mask:0xf bank_mask:0xf
	v_add_f32_dpp v126, v126, v126 quad_perm:[2,3,0,1] row_mask:0xf bank_mask:0xf
	v_add_f32_dpp v127, v127, v127 quad_perm:[2,3,0,1] row_mask:0xf bank_mask:0xf
	v_add_f32_dpp v128, v128, v128 quad_perm:[2,3,0,1] row_mask:0xf bank_mask:0xf
	v_add_f32_dpp v129, v129, v129 quad_perm:[2,3,0,1] row_mask:0xf bank_mask:0xf
	v_add_f32_dpp v130, v130, v130 quad_perm:[2,3,0,1] row_mask:0xf bank_mask:0xf
	v_add_f32_dpp v131, v131, v131 quad_perm:[2,3,0,1] row_mask:0xf bank_mask:0xf
	v_add_f32_dpp v132, v132, v132 quad_perm:[2,3,0,1] row_mask:0xf bank_mask:0xf
	v_add_f32_dpp v133, v133, v133 quad_perm:[2,3,0,1] row_mask:0xf bank_mask:0xf
	v_add_f32_dpp v126, v126, v126 row_half_mirror row_mask:0xf bank_mask:0xf
	v_add_f32_dpp v127, v127, v127 row_half_mirror row_mask:0xf bank_mask:0xf
	v_add_f32_dpp v128, v128, v128 row_half_mirror row_mask:0xf bank_mask:0xf
	v_add_f32_dpp v129, v129, v129 row_half_mirror row_mask:0xf bank_mask:0xf
	v_add_f32_dpp v130, v130, v130 row_half_mirror row_mask:0xf bank_mask:0xf
	v_add_f32_dpp v131, v131, v131 row_half_mirror row_mask:0xf bank_mask:0xf
	v_add_f32_dpp v132, v132, v132 row_half_mirror row_mask:0xf bank_mask:0xf
	v_add_f32_dpp v133, v133, v133 row_half_mirror row_mask:0xf bank_mask:0xf
	v_add_f32_dpp v126, v126, v126 row_mirror row_mask:0xf bank_mask:0xf
	v_add_f32_dpp v127, v127, v127 row_mirror row_mask:0xf bank_mask:0xf
	v_add_f32_dpp v128, v128, v128 row_mirror row_mask:0xf bank_mask:0xf
	v_add_f32_dpp v129, v129, v129 row_mirror row_mask:0xf bank_mask:0xf
	v_add_f32_dpp v130, v130, v130 row_mirror row_mask:0xf bank_mask:0xf
	v_add_f32_dpp v131, v131, v131 row_mirror row_mask:0xf bank_mask:0xf
	v_add_f32_dpp v132, v132, v132 row_mirror row_mask:0xf bank_mask:0xf
	v_add_f32_dpp v133, v133, v133 row_mirror row_mask:0xf bank_mask:0xf
	v_mov_b32_e32 v134, v126
	v_mov_b32_e32 v135, v127
	v_mov_b32_e32 v136, v128
	v_mov_b32_e32 v137, v129
	v_mov_b32_e32 v138, v130
	v_mov_b32_e32 v139, v131
	v_mov_b32_e32 v140, v132
	v_mov_b32_e32 v141, v133
	v_permlane16_swap_b32 v126, v134
	v_permlane16_swap_b32 v127, v135
	v_permlane16_swap_b32 v128, v136
	v_permlane16_swap_b32 v129, v137
	v_permlane16_swap_b32 v130, v138
	v_permlane16_swap_b32 v131, v139
	v_permlane16_swap_b32 v132, v140
	v_permlane16_swap_b32 v133, v141
	v_add_f32_e32 v126, v126, v134
	v_add_f32_e32 v127, v127, v135
	v_add_f32_e32 v128, v128, v136
	v_add_f32_e32 v129, v129, v137
	v_add_f32_e32 v130, v130, v138
	v_add_f32_e32 v131, v131, v139
	v_add_f32_e32 v132, v132, v140
	v_add_f32_e32 v133, v133, v141
	v_mov_b32_e32 v134, v126
	v_mov_b32_e32 v135, v127
	v_mov_b32_e32 v136, v128
	v_mov_b32_e32 v137, v129
	v_mov_b32_e32 v138, v130
	v_mov_b32_e32 v139, v131
	v_mov_b32_e32 v140, v132
	v_mov_b32_e32 v141, v133
	v_permlane32_swap_b32 v126, v134
	v_permlane32_swap_b32 v127, v135
	v_permlane32_swap_b32 v128, v136
	v_permlane32_swap_b32 v129, v137
	v_permlane32_swap_b32 v130, v138
	v_permlane32_swap_b32 v131, v139
	v_permlane32_swap_b32 v132, v140
	v_permlane32_swap_b32 v133, v141
	v_add_f32_e32 v126, v126, v134
	v_add_f32_e32 v127, v127, v135
	v_add_f32_e32 v128, v128, v136
	v_add_f32_e32 v129, v129, v137
	v_add_f32_e32 v130, v130, v138
	v_add_f32_e32 v131, v131, v139
	v_add_f32_e32 v132, v132, v140
	v_add_f32_e32 v133, v133, v141
	v_fmac_f32_e32 v111, 0xbc000000, v126
	v_fmamk_f32 v110, v126, 0xbc000000, v110
	v_fmac_f32_e32 v113, 0xbc000000, v127
	v_fmamk_f32 v112, v127, 0xbc000000, v112
	v_fmac_f32_e32 v115, 0xbc000000, v128
	v_fmamk_f32 v114, v128, 0xbc000000, v114
	v_fmac_f32_e32 v117, 0xbc000000, v129
	v_fmamk_f32 v116, v129, 0xbc000000, v116
	v_fmac_f32_e32 v119, 0xbc000000, v130
	v_fmamk_f32 v118, v130, 0xbc000000, v118
	v_fmac_f32_e32 v121, 0xbc000000, v131
	v_fmamk_f32 v120, v131, 0xbc000000, v120
	v_fmac_f32_e32 v123, 0xbc000000, v132
	v_fmamk_f32 v122, v132, 0xbc000000, v122
	v_fmac_f32_e32 v125, 0xbc000000, v133
	v_fmamk_f32 v124, v133, 0xbc000000, v124
	v_mul_f32_e32 v126, v111, v111
	v_fmac_f32_e32 v126, v110, v110
	v_mul_f32_e32 v127, v113, v113
	v_fmac_f32_e32 v127, v112, v112
	v_mul_f32_e32 v128, v115, v115
	v_fmac_f32_e32 v128, v114, v114
	v_mul_f32_e32 v129, v117, v117
	v_fmac_f32_e32 v129, v116, v116
	v_mul_f32_e32 v130, v119, v119
; __device__ __forceinline__ void conv_phase(LAS unsigned char* lds, const bf16_t* P, const float* cw, const float* cb, const float* ng, const float* nb, bf16_t* CAT, int bid, int G, const int tid) {
;     ...
;                 const float mean = wave_sum(v[0] + v[1]) * (1.0f / 128.0f);
;                 const float d0 = v[0] - mean, d1 = v[1] - mean;
;                 const float rs = __builtin_amdgcn_rsqf(wave_sum(d0 * d0 + d1 * d1) * (1.0f / 128.0f) + EPS);
;                 const float y0 = d0 * rs * gg[0] + bb[0], y1 = d1 * rs * gg[1] + bb[1];
	v_fmac_f32_e32 v130, v118, v118
	v_mul_f32_e32 v131, v121, v121
	v_fmac_f32_e32 v131, v120, v120
	v_mul_f32_e32 v132, v123, v123
	v_fmac_f32_e32 v132, v122, v122
	v_mul_f32_e32 v133, v125, v125
	v_fmac_f32_e32 v133, v124, v124
	v_add_f32_dpp v126, v126, v126 quad_perm:[1,0,3,2] row_mask:0xf bank_mask:0xf
	v_add_f32_dpp v127, v127, v127 quad_perm:[1,0,3,2] row_mask:0xf bank_mask:0xf
	v_add_f32_dpp v128, v128, v128 quad_perm:[1,0,3,2] row_mask:0xf bank_mask:0xf
	v_add_f32_dpp v129, v129, v129 quad_perm:[1,0,3,2] row_mask:0xf bank_mask:0xf
	v_add_f32_dpp v130, v130, v130 quad_perm:[1,0,3,2] row_mask:0xf bank_mask:0xf
	v_add_f32_dpp v131, v131, v131 quad_perm:[1,0,3,2] row_mask:0xf bank_mask:0xf
	v_add_f32_dpp v132, v132, v132 quad_perm:[1,0,3,2] row_mask:0xf bank_mask:0xf
	v_add_f32_dpp v133, v133, v133 quad_perm:[1,0,3,2] row_mask:0xf bank_mask:0xf
	v_add_f32_dpp v126, v126, v126 quad_perm:[2,3,0,1] row_mask:0xf bank_mask:0xf
	v_add_f32_dpp v127, v127, v127 quad_perm:[2,3,0,1] row_mask:0xf bank_mask:0xf
	v_add_f32_dpp v128, v128, v128 quad_perm:[2,3,0,1] row_mask:0xf bank_mask:0xf
	v_add_f32_dpp v129, v129, v129 quad_perm:[2,3,0,1] row_mask:0xf bank_mask:0xf
	v_add_f32_dpp v130, v130, v130 quad_perm:[2,3,0,1] row_mask:0xf bank_mask:0xf
	v_add_f32_dpp v131, v131, v131 quad_perm:[2,3,0,1] row_mask:0xf bank_mask:0xf
	v_add_f32_dpp v132, v132, v132 quad_perm:[2,3,0,1] row_mask:0xf bank_mask:0xf
	v_add_f32_dpp v133, v133, v133 quad_perm:[2,3,0,1] row_mask:0xf bank_mask:0xf
	v_add_f32_dpp v126, v126, v126 row_half_mirror row_mask:0xf bank_mask:0xf
	v_add_f32_dpp v127, v127, v127 row_half_mirror row_mask:0xf bank_mask:0xf
	v_add_f32_dpp v128, v128, v128 row_half_mirror row_mask:0xf bank_mask:0xf
	v_add_f32_dpp v129, v129, v129 row_half_mirror row_mask:0xf bank_mask:0xf
	v_add_f32_dpp v130, v130, v130 row_half_mirror row_mask:0xf bank_mask:0xf
	v_add_f32_dpp v131, v131, v131 row_half_mirror row_mask:0xf bank_mask:0xf
	v_add_f32_dpp v132, v132, v132 row_half_mirror row_mask:0xf bank_mask:0xf
	v_add_f32_dpp v133, v133, v133 row_half_mirror row_mask:0xf bank_mask:0xf
	v_add_f32_dpp v126, v126, v126 row_mirror row_mask:0xf bank_mask:0xf
	v_add_f32_dpp v127, v127, v127 row_mirror row_mask:0xf bank_mask:0xf
	v_add_f32_dpp v128, v128, v128 row_mirror row_mask:0xf bank_mask:0xf
	v_add_f32_dpp v129, v129, v129 row_mirror row_mask:0xf bank_mask:0xf
	v_add_f32_dpp v130, v130, v130 row_mirror row_mask:0xf bank_mask:0xf
	v_add_f32_dpp v131, v131, v131 row_mirror row_mask:0xf bank_mask:0xf
	v_add_f32_dpp v132, v132, v132 row_mirror row_mask:0xf bank_mask:0xf
	v_add_f32_dpp v133, v133, v133 row_mirror row_mask:0xf bank_mask:0xf
	v_mov_b32_e32 v134, v126
	v_mov_b32_e32 v135, v127
	v_mov_b32_e32 v136, v128
	v_mov_b32_e32 v137, v129
	v_mov_b32_e32 v138, v130
	v_mov_b32_e32 v139, v131
	v_mov_b32_e32 v140, v132
	v_mov_b32_e32 v141, v133
	v_permlane16_swap_b32 v126, v134
	v_permlane16_swap_b32 v127, v135
	v_permlane16_swap_b32 v128, v136
	v_permlane16_swap_b32 v129, v137
	v_permlane16_swap_b32 v130, v138
	v_permlane16_swap_b32 v131, v139
	v_permlane16_swap_b32 v132, v140
	v_permlane16_swap_b32 v133, v141
	v_add_f32_e32 v126, v126, v134
	v_add_f32_e32 v127, v127, v135
	v_add_f32_e32 v128, v128, v136
	v_add_f32_e32 v129, v129, v137
	v_add_f32_e32 v130, v130, v138
	v_add_f32_e32 v131, v131, v139
	v_add_f32_e32 v132, v132, v140
	v_add_f32_e32 v133, v133, v141
	v_mov_b32_e32 v134, v126
	v_mov_b32_e32 v135, v127
	v_mov_b32_e32 v136, v128
	v_mov_b32_e32 v137, v129
	v_mov_b32_e32 v138, v130
	v_mov_b32_e32 v139, v131
	v_mov_b32_e32 v140, v132
	v_mov_b32_e32 v141, v133
	v_permlane32_swap_b32 v126, v134
	v_permlane32_swap_b32 v127, v135
	v_permlane32_swap_b32 v128, v136
	v_permlane32_swap_b32 v129, v137
	v_permlane32_swap_b32 v130, v138
	v_permlane32_swap_b32 v131, v139
	v_permlane32_swap_b32 v132, v140
	v_permlane32_swap_b32 v133, v141
	v_add_f32_e32 v126, v126, v134
	v_add_f32_e32 v127, v127, v135
	v_add_f32_e32 v128, v128, v136
	v_add_f32_e32 v129, v129, v137
	v_add_f32_e32 v130, v130, v138
	v_add_f32_e32 v131, v131, v139
	v_add_f32_e32 v132, v132, v140
	v_add_f32_e32 v133, v133, v141
	v_fmamk_f32 v126, v126, 0x3c000000, v189
	v_fmamk_f32 v127, v127, 0x3c000000, v189
	v_fmamk_f32 v128, v128, 0x3c000000, v189
	v_fmamk_f32 v129, v129, 0x3c000000, v189
	v_fmamk_f32 v130, v130, 0x3c000000, v189
	v_fmamk_f32 v131, v131, 0x3c000000, v189
	v_fmamk_f32 v132, v132, 0x3c000000, v189
	v_fmamk_f32 v133, v133, 0x3c000000, v189
	v_rsq_f32_e32 v126, v126
	v_rsq_f32_e32 v127, v127
	v_rsq_f32_e32 v128, v128
	v_rsq_f32_e32 v129, v129
	v_rsq_f32_e32 v130, v130
	v_rsq_f32_e32 v131, v131
	v_rsq_f32_e32 v132, v132
	v_rsq_f32_e32 v133, v133
	v_mul_f32_e32 v110, v110, v126
	v_mul_f32_e32 v111, v111, v126
	v_mul_f32_e32 v112, v112, v127
	v_mul_f32_e32 v113, v113, v127
	v_mul_f32_e32 v114, v114, v128
	v_mul_f32_e32 v115, v115, v128
	v_mul_f32_e32 v116, v116, v129
	v_mul_f32_e32 v117, v117, v129
	v_mul_f32_e32 v118, v118, v130
	v_mul_f32_e32 v119, v119, v130
	v_mul_f32_e32 v120, v120, v131
	v_mul_f32_e32 v121, v121, v131
	v_mul_f32_e32 v122, v122, v132
	v_mul_f32_e32 v123, v123, v132
	v_mul_f32_e32 v124, v124, v133
	v_mul_f32_e32 v125, v125, v133
	v_fma_f32 v110, v150, v110, v152
	v_fma_f32 v111, v151, v111, v153
	v_fma_f32 v112, v150, v112, v152
	v_fma_f32 v113, v151, v113, v153
	v_fma_f32 v114, v150, v114, v152
	v_fma_f32 v115, v151, v115, v153
	v_fma_f32 v116, v150, v116, v152
; __device__ __forceinline__ unsigned cvt_pk_bf16(float lo, float hi) { unsigned r; asm("v_cvt_pk_bf16_f32 %0, %1, %2" : "=v"(r) : "v"(lo), "v"(hi)); return r; }
; __device__ __forceinline__ float fast_sigmoid(float x) { return __builtin_amdgcn_rcpf(1.0f + __builtin_amdgcn_exp2f(-1.4426950408889634f * x)); }
; __device__ __forceinline__ float silu_f(float x) { return x * fast_sigmoid(x); }
; __device__ __forceinline__ void conv_phase(LAS unsigned char* lds, const bf16_t* P, const float* cw, const float* cb, const float* ng, const float* nb, bf16_t* CAT, int bid, int G, const int tid) {
;     ...
;                 const float y0 = d0 * rs * gg[0] + bb[0], y1 = d1 * rs * gg[1] + bb[1];
;                 *(unsigned*)(CAT + (size_t)(b * SEQ + t0 + tok) * D + 1024 + g * 128 + 2 * lane) = cvt_pk_bf16(silu_f(y0), silu_f(y1));
	v_fma_f32 v117, v151, v117, v153
	v_fma_f32 v118, v150, v118, v152
	v_fma_f32 v119, v151, v119, v153
	v_fma_f32 v120, v150, v120, v152
	v_fma_f32 v121, v151, v121, v153
	v_fma_f32 v122, v150, v122, v152
	v_fma_f32 v123, v151, v123, v153
	v_fma_f32 v124, v150, v124, v152
	v_fma_f32 v125, v151, v125, v153
	v_mul_f32_e32 v134, 0xbfb8aa3b, v110
	v_mul_f32_e32 v142, 0xbfb8aa3b, v111
	v_mul_f32_e32 v135, 0xbfb8aa3b, v112
	v_mul_f32_e32 v143, 0xbfb8aa3b, v113
	v_mul_f32_e32 v136, 0xbfb8aa3b, v114
	v_mul_f32_e32 v144, 0xbfb8aa3b, v115
	v_mul_f32_e32 v137, 0xbfb8aa3b, v116
	v_mul_f32_e32 v145, 0xbfb8aa3b, v117
	v_mul_f32_e32 v138, 0xbfb8aa3b, v118
	v_mul_f32_e32 v146, 0xbfb8aa3b, v119
	v_mul_f32_e32 v139, 0xbfb8aa3b, v120
	v_mul_f32_e32 v147, 0xbfb8aa3b, v121
	v_mul_f32_e32 v140, 0xbfb8aa3b, v122
	v_mul_f32_e32 v148, 0xbfb8aa3b, v123
	v_mul_f32_e32 v141, 0xbfb8aa3b, v124
	v_mul_f32_e32 v149, 0xbfb8aa3b, v125
	v_exp_f32_e32 v134, v134
	v_exp_f32_e32 v142, v142
	v_exp_f32_e32 v135, v135
	v_exp_f32_e32 v143, v143
	v_exp_f32_e32 v136, v136
	v_exp_f32_e32 v144, v144
	v_exp_f32_e32 v137, v137
	v_exp_f32_e32 v145, v145
	v_exp_f32_e32 v138, v138
	v_exp_f32_e32 v146, v146
	v_exp_f32_e32 v139, v139
	v_exp_f32_e32 v147, v147
	v_exp_f32_e32 v140, v140
	v_exp_f32_e32 v148, v148
	v_exp_f32_e32 v141, v141
	v_exp_f32_e32 v149, v149
	s_nop 0
	v_add_f32_e32 v134, 1.0, v134
	v_add_f32_e32 v142, 1.0, v142
	v_add_f32_e32 v135, 1.0, v135
	v_add_f32_e32 v143, 1.0, v143
	v_add_f32_e32 v136, 1.0, v136
	v_add_f32_e32 v144, 1.0, v144
	v_add_f32_e32 v137, 1.0, v137
	v_add_f32_e32 v145, 1.0, v145
	v_add_f32_e32 v138, 1.0, v138
	v_add_f32_e32 v146, 1.0, v146
	v_add_f32_e32 v139, 1.0, v139
	v_add_f32_e32 v147, 1.0, v147
	v_add_f32_e32 v140, 1.0, v140
	v_add_f32_e32 v148, 1.0, v148
	v_add_f32_e32 v141, 1.0, v141
	v_add_f32_e32 v149, 1.0, v149
	v_rcp_f32_e32 v134, v134
	v_rcp_f32_e32 v142, v142
	v_rcp_f32_e32 v135, v135
	v_rcp_f32_e32 v143, v143
	v_rcp_f32_e32 v136, v136
	v_rcp_f32_e32 v144, v144
	v_rcp_f32_e32 v137, v137
	v_rcp_f32_e32 v145, v145
	v_rcp_f32_e32 v138, v138
	v_rcp_f32_e32 v146, v146
	v_rcp_f32_e32 v139, v139
	v_rcp_f32_e32 v147, v147
	v_rcp_f32_e32 v140, v140
	v_rcp_f32_e32 v148, v148
	v_rcp_f32_e32 v141, v141
	v_rcp_f32_e32 v149, v149
	s_nop 0
	v_mul_f32_e32 v110, v110, v134
	v_mul_f32_e32 v111, v111, v142
	v_mul_f32_e32 v112, v112, v135
	v_mul_f32_e32 v113, v113, v143
	v_mul_f32_e32 v114, v114, v136
	v_mul_f32_e32 v115, v115, v144
	v_mul_f32_e32 v116, v116, v137
	v_mul_f32_e32 v117, v117, v145
	v_mul_f32_e32 v118, v118, v138
	v_mul_f32_e32 v119, v119, v146
	v_mul_f32_e32 v120, v120, v139
	v_mul_f32_e32 v121, v121, v147
	v_mul_f32_e32 v122, v122, v140
	v_mul_f32_e32 v123, v123, v148
	v_mul_f32_e32 v124, v124, v141
	v_mul_f32_e32 v125, v125, v149
	v_cvt_pk_bf16_f32 v134, v110, v111
	v_cvt_pk_bf16_f32 v135, v112, v113
	v_cvt_pk_bf16_f32 v136, v114, v115
	v_cvt_pk_bf16_f32 v137, v116, v117
	v_cvt_pk_bf16_f32 v138, v118, v119
	v_cvt_pk_bf16_f32 v139, v120, v121
	v_cvt_pk_bf16_f32 v140, v122, v123
	v_cvt_pk_bf16_f32 v141, v124, v125
	v_add_u32_e32 v66, s31, v41
	v_ashrrev_i32_e32 v67, 31, v66
	v_lshlrev_b64 v[66:67], 12, v[66:67]
	v_lshl_add_u64 v[66:67], s[92:93], 0, v[66:67]
	v_lshl_add_u64 v[66:67], v[66:67], 0, s[26:27]
	v_lshl_add_u64 v[66:67], v[66:67], 0, v[30:31]
	global_store_dword v[66:67], v134, off offset:2048
	v_add_u32_e32 v66, s31, v51
	v_ashrrev_i32_e32 v67, 31, v66
	v_lshlrev_b64 v[66:67], 12, v[66:67]
	v_lshl_add_u64 v[66:67], s[92:93], 0, v[66:67]
	v_lshl_add_u64 v[66:67], v[66:67], 0, s[26:27]
	v_lshl_add_u64 v[66:67], v[66:67], 0, v[30:31]
	global_store_dword v[66:67], v135, off offset:2048
	v_add_u32_e32 v66, s31, v52
	v_ashrrev_i32_e32 v67, 31, v66
	v_lshlrev_b64 v[66:67], 12, v[66:67]
	v_lshl_add_u64 v[66:67], s[92:93], 0, v[66:67]
	v_lshl_add_u64 v[66:67], v[66:67], 0, s[26:27]
	v_lshl_add_u64 v[66:67], v[66:67], 0, v[30:31]
	global_store_dword v[66:67], v136, off offset:2048
	v_add_u32_e32 v66, s31, v53
	v_ashrrev_i32_e32 v67, 31, v66
	v_lshlrev_b64 v[66:67], 12, v[66:67]
	v_lshl_add_u64 v[66:67], s[92:93], 0, v[66:67]
	v_lshl_add_u64 v[66:67], v[66:67], 0, s[26:27]
	v_lshl_add_u64 v[66:67], v[66:67], 0, v[30:31]
	global_store_dword v[66:67], v137, off offset:2048
	v_add_u32_e32 v66, s31, v54
	v_ashrrev_i32_e32 v67, 31, v66
	v_lshlrev_b64 v[66:67], 12, v[66:67]
	v_lshl_add_u64 v[66:67], s[92:93], 0, v[66:67]
	v_lshl_add_u64 v[66:67], v[66:67], 0, s[26:27]
	v_lshl_add_u64 v[66:67], v[66:67], 0, v[30:31]
	global_store_dword v[66:67], v138, off offset:2048
	v_add_u32_e32 v66, s31, v55
	v_ashrrev_i32_e32 v67, 31, v66
	v_lshlrev_b64 v[66:67], 12, v[66:67]
	v_lshl_add_u64 v[66:67], s[92:93], 0, v[66:67]
	v_lshl_add_u64 v[66:67], v[66:67], 0, s[26:27]
	v_lshl_add_u64 v[66:67], v[66:67], 0, v[30:31]
	global_store_dword v[66:67], v139, off offset:2048
	v_add_u32_e32 v66, s31, v56
	v_ashrrev_i32_e32 v67, 31, v66
	v_lshlrev_b64 v[66:67], 12, v[66:67]
	v_lshl_add_u64 v[66:67], s[92:93], 0, v[66:67]
	v_lshl_add_u64 v[66:67], v[66:67], 0, s[26:27]
	v_lshl_add_u64 v[66:67], v[66:67], 0, v[30:31]
	global_store_dword v[66:67], v140, off offset:2048
	v_add_u32_e32 v66, s31, v57
	v_ashrrev_i32_e32 v67, 31, v66
	v_lshlrev_b64 v[66:67], 12, v[66:67]
	v_lshl_add_u64 v[66:67], s[92:93], 0, v[66:67]
	v_lshl_add_u64 v[66:67], v[66:67], 0, s[26:27]
	v_lshl_add_u64 v[66:67], v[66:67], 0, v[30:31]
	global_store_dword v[66:67], v141, off offset:2048
	s_cbranch_vccz .LBB0_186
